# v91 + kernarg scalar loads merged into one round trip at entry (incl. the 0x80 block previously loaded at the end of P0)
# speedup vs baseline: 1.0037x; 1.0037x over previous
; #define LAS __attribute__((address_space(3)))
; __global__ void __launch_bounds__(NWAVES * 64, 2) mk_fwd(Args args) {
;     extern __shared__ __attribute__((aligned(16))) unsigned char lds[];
;     Frame F;
;     F.lds = (LAS unsigned char*)lds;
;     F.tid = threadIdx.x; F.lane = F.tid & 63; F.wave = __builtin_amdgcn_readfirstlane(F.tid >> 6);
;     F.G = gridDim.x; F.bid = blockIdx.x;
; #pragma unroll
;     for (int i = 0; i < 24; ++i) F.in[i] = args.in[i];
;     F.out = args.out; F.ws = args.ws;
;     const int lo = args.ph_lo, hi = args.ph_hi;
;     ...
;     volatile LAS unsigned* MISC = (volatile LAS unsigned*)(F.lds + MISC_OFF);
;     if (F.tid < 32) MISC[F.tid] = 0u;
;     __syncthreads();
;     XcdBarrier bar = xcd_barrier_post((unsigned*)(F.ws + WS_CTL) + CW_BAR, MISC + 8);
_Z6mk_fwd4Args:
	s_load_dword s52, s[0:1], 0xd8
	s_load_dwordx4 s[48:51], s[0:1], 0xc0
	s_load_dwordx2 s[22:23], s[0:1], 0xd0
	s_load_dwordx16 s[4:19], s[0:1], 0x0
	s_load_dwordx16 s[80:95], s[0:1], 0x40
	s_load_dwordx16 s[56:71], s[0:1], 0x80
	v_readfirstlane_b32 s20, v0
	v_cmp_gt_u32_e32 vcc, 32, v0
	s_waitcnt lgkmcnt(0)
	v_writelane_b32 v238, s22, 0
	s_nop 1
	v_writelane_b32 v238, s23, 1
	s_add_u32 s24, s0, 0xd8
	s_addc_u32 s25, s1, 0
	v_writelane_b32 v238, s24, 2
	s_nop 1
	v_writelane_b32 v238, s25, 3
	s_and_saveexec_b64 s[24:25], vcc
	v_lshl_add_u32 v1, v0, 2, 0
	v_add_u32_e32 v1, 0x24200, v1
	v_mov_b32_e32 v2, 0
	ds_write_b32 v1, v2
	s_or_b64 exec, exec, s[24:25]
	v_writelane_b32 v238, s56, 29
	v_writelane_b32 v238, s57, 30
	v_writelane_b32 v238, s58, 31
	v_writelane_b32 v238, s59, 32
	v_writelane_b32 v238, s60, 33
	v_writelane_b32 v238, s61, 34
	v_writelane_b32 v238, s62, 35
	v_writelane_b32 v238, s63, 36
	v_writelane_b32 v238, s64, 37
	v_writelane_b32 v238, s65, 38
	v_writelane_b32 v238, s66, 39
	v_writelane_b32 v238, s67, 40
	v_writelane_b32 v238, s68, 41
	v_writelane_b32 v238, s69, 42
	v_writelane_b32 v238, s70, 43
	v_writelane_b32 v238, s71, 44
	s_waitcnt lgkmcnt(0)
	s_barrier
	v_writelane_b32 v238, s4, 4
	s_getreg_b32 s3, hwreg(HW_REG_XCC_ID, 0, 4)
	s_nop 0
	v_writelane_b32 v238, s5, 5
	v_writelane_b32 v238, s6, 6
	v_writelane_b32 v238, s7, 7
	v_writelane_b32 v238, s8, 8
	v_writelane_b32 v238, s9, 9
	v_writelane_b32 v238, s10, 10
	v_writelane_b32 v238, s11, 11
	v_writelane_b32 v238, s12, 12
	v_writelane_b32 v238, s13, 13
	v_writelane_b32 v238, s14, 14
	v_writelane_b32 v238, s15, 15
	v_writelane_b32 v238, s16, 16
	v_writelane_b32 v238, s17, 17
	v_writelane_b32 v238, s18, 18
	v_writelane_b32 v238, s19, 19
	s_add_u32 s4, s50, 0x4000
	s_addc_u32 s5, s51, 0
	v_writelane_b32 v238, s4, 20
	s_and_b32 s3, s3, 15
	v_cmp_eq_u32_e64 s[6:7], 0, v0
	v_writelane_b32 v238, s5, 21
	v_writelane_b32 v238, s3, 22
	s_mov_b64 s[4:5], exec
	v_writelane_b32 v238, s6, 23
	s_nop 1
	v_writelane_b32 v238, s7, 24
	s_and_b64 s[6:7], s[4:5], s[6:7]
	s_mov_b64 exec, s[6:7]
	s_cbranch_execz .LBB0_5
	s_mov_b64 s[6:7], exec
	v_mbcnt_lo_u32_b32 v1, s6, 0
	v_mbcnt_hi_u32_b32 v1, s7, v1
	v_cmp_eq_u32_e32 vcc, 0, v1
	s_and_b64 s[8:9], exec, vcc
	s_mov_b64 exec, s[8:9]
	s_cbranch_execz .LBB0_5
	v_readlane_b32 s3, v238, 22
	s_bcnt1_i32_b64 s6, s[6:7]
	s_lshl_b32 s3, s3, 8
	v_mov_b32_e32 v2, s6
	v_readlane_b32 s6, v238, 20
	v_mov_b32_e32 v1, s3
	v_readlane_b32 s7, v238, 21
	s_nop 4
	global_atomic_add v1, v2, s[6:7] offset:1024
; #define LAS __attribute__((address_space(3)))
; __device__ __forceinline__ void p0_prologue(Frame& F) {
;     ...
;     S5TabRegs TR; if (F.G == 256) s5_tables_fetch(F, F.bid, TR);
;     if (NGW == 2048) {
;         f32x4 xv[9][4]; const bool xe = gw < MS;
;         rms9_issue(F.in[0] + (size_t)(8 * gw) * DM, xe ? F.in[1] + (size_t)gw * DM : nullptr, xv, F.lane);
;         const int wr_ = F.bid + 256 * F.wave; const bool hasw = wr_ < I_IN;
;         const int nblk_ = INC / 64, kb_ = wr_ / nblk_, sn0_ = (wr_ % nblk_) * 64, seg_ = sn0_ / 512;
;         const int dseg_ = seg_ == 0 ? 0 : seg_ == 1 ? 1 : seg_ == 2 ? 4 : seg_ == 3 ? 2 : 3;
;         LAS unsigned char* IMG = F.lds + 98304 + (F.wave < 3 ? F.wave : 0) * 16384;
;         if (hasw) transpose_issue_lds(F.in[7], INC, kb_ * 64, sn0_, F.lane, IMG);
;         s5_tables_item(F, F.bid, TR);
;         rms9_finish(xv, xe, F.in[6], XN + (size_t)(8 * gw) * DM, XN + (size_t)(MP + gw) * DM, F.lane);
;         if (hasw) transpose_finish_lds((bf16*)(F.ws + WS_WIN), DM, kb_ * 64, dseg_ * 512 + sn0_ % 512, F.lane, IMG, F.lds + F.wave * 8192);
;     } else {
; __global__ void __launch_bounds__(NWAVES * 64, 2) mk_fwd(Args args) {
;     ...
;     const int lo = args.ph_lo, hi = args.ph_hi;
.LBB0_5:
	s_or_b64 exec, exec, s[4:5]
	v_readlane_b32 s6, v238, 0
	v_readlane_b32 s7, v238, 1
	s_lshr_b32 s96, s20, 6
	s_lshl_b32 s3, s2, 3
	s_add_i32 s34, s3, s96
	s_lshl_b32 s18, s52, 3
	s_add_u32 s46, s50, 0x1b00000
	s_addc_u32 s47, s51, 0
	s_waitcnt lgkmcnt(0)
	s_cmp_lt_i32 s6, 1
	s_cselect_b64 s[4:5], -1, 0
	s_cmp_gt_i32 s7, 0
	s_cselect_b64 s[6:7], -1, 0
	s_and_b64 s[72:73], s[4:5], s[6:7]
	s_andn2_b64 vcc, exec, s[72:73]
	v_and_b32_e32 v154, 63, v0
	v_writelane_b32 v238, s20, 25
	s_cbranch_vccnz .LBB0_71
	s_cmpk_lg_i32 s52, 0x100
	s_cselect_b64 s[12:13], -1, 0
	s_mov_b64 s[4:5], -1
	s_and_b64 vcc, exec, s[12:13]
	v_or_b32_e32 v150, 64, v154
	s_cbranch_vccnz .LBB0_43
	s_ashr_i32 s4, s2, 3
	s_lshl_b32 s3, s4, 6
	v_or_b32_e32 v2, s3, v154
	v_ashrrev_i32_e32 v3, 31, v2
	s_ashr_i32 s5, s4, 31
	v_lshlrev_b64 v[2:3], 2, v[2:3]
	s_lshl_b64 s[6:7], s[4:5], 2
	v_lshl_add_u64 v[4:5], s[80:81], 0, v[2:3]
	v_lshl_add_u64 v[2:3], s[82:83], 0, v[2:3]
	s_add_u32 s6, s84, s6
	global_load_dword v165, v[2:3], off
	s_addc_u32 s7, s85, s7
	s_lshl_b32 s5, s4, 4
	v_lshrrev_b32_e32 v3, 6, v0
	global_load_dword v164, v[4:5], off
	v_or_b32_e32 v4, s5, v3
	v_ashrrev_i32_e32 v5, 31, v4
	v_lshlrev_b64 v[4:5], 8, v[4:5]
	v_lshlrev_b32_e32 v146, 2, v154
	v_or_b32_e32 v4, v4, v146
	v_lshl_add_u64 v[6:7], s[90:91], 0, v[4:5]
	v_lshl_add_u64 v[4:5], s[92:93], 0, v[4:5]
	v_lshrrev_b32_e32 v158, 4, v0
	global_load_dword v149, v[4:5], off
	v_or_b32_e32 v4, s3, v158
	v_and_b32_e32 v1, 15, v0
	v_ashrrev_i32_e32 v5, 31, v4
	v_lshlrev_b64 v[4:5], 6, v[4:5]
	v_lshlrev_b32_e32 v147, 2, v1
	s_load_dwordx16 s[56:71], s[0:1], 0x0
	v_or_b32_e32 v4, v4, v147
	v_or_b32_e32 v148, 0x200, v0
	global_load_dword v153, v[6:7], off
	v_lshl_add_u64 v[6:7], s[86:87], 0, v[4:5]
	v_lshl_add_u64 v[4:5], s[88:89], 0, v[4:5]
	v_lshrrev_b32_e32 v3, 6, v148
	s_lshl_b32 s22, s34, 3
	v_mov_b32_e32 v2, 0
	global_load_dword v157, v[4:5], off
	v_or_b32_e32 v4, s5, v3
	s_ashr_i32 s23, s22, 31
	global_load_dword v166, v2, s[6:7]
	v_ashrrev_i32_e32 v5, 31, v4
	s_lshl_b64 s[6:7], s[22:23], 12
	v_lshlrev_b64 v[4:5], 8, v[4:5]
	s_waitcnt lgkmcnt(0)
	s_add_u32 s8, s56, s6
	v_or_b32_e32 v4, v4, v146
	s_addc_u32 s9, s57, s7
	s_ashr_i32 s35, s34, 31
	global_load_dword v156, v[6:7], off
	v_lshl_add_u64 v[6:7], s[90:91], 0, v[4:5]
	v_lshl_add_u64 v[4:5], s[92:93], 0, v[4:5]
	v_lshrrev_b32_e32 v161, 4, v148
	s_lshl_b64 s[6:7], s[34:35], 12
	global_load_dword v159, v[4:5], off
	v_or_b32_e32 v4, s3, v161
	s_add_u32 s3, s58, s6
	s_addc_u32 s5, s59, s7
	s_cmpk_lt_i32 s34, 0x400
	s_cselect_b64 s[20:21], -1, 0
	s_and_b64 s[6:7], s[20:21], exec
	s_cselect_b32 s7, s5, 0
	s_cselect_b32 s6, s3, 0
	s_add_u32 s10, s8, 0x1000
	s_addc_u32 s11, s9, 0
	s_add_u32 s14, s8, 0x2000
	s_addc_u32 s15, s9, 0
	s_add_u32 s16, s8, 0x3000
	s_addc_u32 s17, s9, 0
	s_add_u32 s24, s8, 0x4000
	s_addc_u32 s25, s9, 0
	s_add_u32 s26, s8, 0x5000
	v_ashrrev_i32_e32 v5, 31, v4
	s_addc_u32 s27, s9, 0
	v_lshlrev_b64 v[4:5], 6, v[4:5]
	s_add_u32 s28, s8, 0x6000
	v_or_b32_e32 v4, v4, v147
	s_addc_u32 s29, s9, 0
	global_load_dword v160, v[6:7], off
	v_lshl_add_u64 v[6:7], s[86:87], 0, v[4:5]
	v_lshl_add_u64 v[4:5], s[88:89], 0, v[4:5]
	v_or_b32_e32 v155, 0x80, v154
	v_or_b32_e32 v151, 0xc0, v154
	v_lshlrev_b32_e32 v3, 4, v150
	s_add_u32 s30, s8, 0x7000
	global_load_dword v162, v[6:7], off
	global_load_dword v163, v[4:5], off
	v_lshlrev_b32_e32 v152, 4, v154
	v_lshlrev_b32_e32 v4, 4, v155
	v_lshlrev_b32_e32 v5, 4, v151
	global_load_dwordx4 v[90:93], v3, s[10:11] nt
	global_load_dwordx4 v[82:85], v3, s[14:15] nt
	global_load_dwordx4 v[86:89], v3, s[16:17] nt
	global_load_dwordx4 v[78:81], v3, s[24:25] nt
	s_addc_u32 s31, s9, 0
	global_load_dwordx4 v[102:105], v3, s[26:27] nt
	global_load_dwordx4 v[98:101], v3, s[28:29] nt
	global_load_dwordx4 v[94:97], v3, s[30:31] nt
	global_load_dwordx4 v[66:69], v4, s[10:11] nt
	global_load_dwordx4 v[62:65], v4, s[14:15] nt
	global_load_dwordx4 v[58:61], v4, s[16:17] nt
	global_load_dwordx4 v[54:57], v4, s[24:25] nt
	global_load_dwordx4 v[50:53], v4, s[26:27] nt
	global_load_dwordx4 v[46:49], v4, s[28:29] nt
	global_load_dwordx4 v[42:45], v4, s[30:31] nt
	global_load_dwordx4 v[34:37], v5, s[10:11] nt
	global_load_dwordx4 v[30:33], v5, s[14:15] nt
	global_load_dwordx4 v[26:29], v5, s[16:17] nt
	global_load_dwordx4 v[22:25], v5, s[24:25] nt
	global_load_dwordx4 v[18:21], v5, s[26:27] nt
	global_load_dwordx4 v[14:17], v5, s[28:29] nt
	global_load_dwordx4 v[6:9], v5, s[30:31] nt
	global_load_dwordx4 v[142:145], v152, s[8:9] nt
	global_load_dwordx4 v[106:109], v152, s[8:9] offset:1024 nt
	global_load_dwordx4 v[70:73], v152, s[8:9] offset:2048 nt
	global_load_dwordx4 v[38:41], v152, s[8:9] offset:3072 nt
	global_load_dwordx4 v[138:141], v152, s[10:11] nt
	global_load_dwordx4 v[134:137], v152, s[14:15] nt
	global_load_dwordx4 v[130:133], v152, s[16:17] nt
	global_load_dwordx4 v[126:129], v152, s[24:25] nt
	global_load_dwordx4 v[122:125], v152, s[26:27] nt
	global_load_dwordx4 v[118:121], v152, s[28:29] nt
	global_load_dwordx4 v[114:117], v152, s[30:31] nt
	s_cmp_lg_u64 s[6:7], 0
	s_cselect_b64 s[8:9], -1, 0
	s_cmp_eq_u64 s[6:7], 0
	v_mov_b32_e32 v110, 0
	v_mov_b32_e32 v111, 0
	v_mov_b32_e32 v112, 0
	v_mov_b32_e32 v113, 0
	v_mov_b32_e32 v74, 0
	v_mov_b32_e32 v75, 0
	v_mov_b32_e32 v76, 0
	v_mov_b32_e32 v77, 0
	s_cbranch_scc1 .LBB0_9
	global_load_dwordx4 v[110:113], v152, s[6:7] nt
	global_load_dwordx4 v[74:77], v152, s[6:7] offset:1024 nt

; __device__ __forceinline__ unsigned xb_add(unsigned* p, unsigned v) { return __hip_atomic_fetch_add(p, v, __ATOMIC_RELAXED, __HIP_MEMORY_SCOPE_AGENT); }
; #define SEAM(k) do { if (IN(k) && IN((k) + 1)) { xcd_barrier(bar); if (F.bid == 0 && F.tid == 0) { const unsigned long long t_ = __builtin_amdgcn_s_memtime(); MISC[32 + 2 * ((k) + 1)] = (unsigned)t_; MISC[33 + 2 * ((k) + 1)] = (unsigned)(t_ >> 32); } } } while (0)
; #define SEAM(k) do { if (IN(k) && IN((k) + 1)) { xcd_barrier(bar); if (F.bid == 0 && F.tid == 0) { const unsigned long long t_ = __builtin_amdgcn_s_memrealtime(); MISC[32 + 2 * ((k) + 1)] = (unsigned)t_; MISC[33 + 2 * ((k) + 1)] = (unsigned)(t_ >> 32); } } } while (0)
; #define SEAM(k) do { if (IN(k) && IN((k) + 1)) { xcd_barrier(bar); xcd_barrier(bar); } } while (0)
; #define SEAM(k) do { if (IN(k) && IN((k) + 1)) xcd_barrier(bar); } while (0)
; #define SEAM(k) do { } while (0)
; __device__ __forceinline__ void xcd_barrier(const XcdBarrier& b) {
;     asm volatile("s_waitcnt vmcnt(0)" ::: "memory");
;     __syncthreads();
;     if (threadIdx.x == 0) {
;         unsigned* bar = b.bar;
;         __builtin_amdgcn_s_waitcnt(0);
;         unsigned nloc = b.st[0], nx = b.st[1];
;         if (nloc == 0u) { xcd_barrier_complete(bar, b.x, nloc, nx); b.st[0] = nloc; b.st[1] = nx; }
;         const unsigned old = xb_add(&bar[XB_XSUB(b.x)], 1u);
;         const unsigned gen = old / nloc;
;         if (old + 1u == (gen + 1u) * nloc) {
; __global__ void __launch_bounds__(NWAVES * 64, 2) mk_fwd(Args args) {
;     ...
;     } SEAM(0);
.LBB0_71:
	v_writelane_b32 v238, s34, 26
	s_nop 1
	v_writelane_b32 v238, s35, 27
	v_writelane_b32 v238, s18, 28
	s_nop 0
	v_readlane_b32 s0, v238, 0
	v_readlane_b32 s1, v238, 1
	s_cmp_gt_i32 s1, 1
	s_cselect_b64 s[4:5], -1, 0
	s_and_b64 s[0:1], s[72:73], s[4:5]
	s_andn2_b64 vcc, exec, s[0:1]
	s_cbranch_vccnz .LBB0_127
	s_waitcnt vmcnt(0)
	s_barrier
	s_mov_b64 s[6:7], exec
	v_readlane_b32 s0, v238, 23
	v_readlane_b32 s1, v238, 24
	s_and_b64 s[0:1], s[6:7], s[0:1]
	s_mov_b64 exec, s[0:1]
	s_cbranch_execz .LBB0_126
	s_add_i32 s0, 0, 0x24220
	v_mov_b32_e32 v1, s0
	s_waitcnt vmcnt(0) expcnt(0) lgkmcnt(0)
	ds_read_b32 v3, v1
	s_add_i32 s0, 0, 0x24224
	v_mov_b32_e32 v1, s0
	ds_read_b32 v1, v1
	s_waitcnt lgkmcnt(1)
	v_cmp_ne_u32_e32 vcc, 0, v3
	s_cbranch_vccnz .LBB0_88
	v_readlane_b32 s0, v238, 2
	v_readlane_b32 s1, v238, 3
	s_load_dwordx2 s[10:11], s[0:1], 0x4
	s_add_u32 s0, s50, 0x4200
	s_addc_u32 s1, s51, 0
	s_add_u32 s8, s50, 0x4400
	s_addc_u32 s9, s51, 0
	s_waitcnt lgkmcnt(0)
	s_mul_i32 s3, s10, s52
	s_add_u32 s10, s50, 0x4500
	s_mul_i32 s3, s3, s11
	s_addc_u32 s11, s51, 0
	s_add_u32 s12, s50, 0x4600
	s_addc_u32 s13, s51, 0
	s_add_u32 s14, s50, 0x4700
	s_addc_u32 s15, s51, 0
	s_add_u32 s16, s50, 0x4800
	s_addc_u32 s17, s51, 0
	s_add_u32 s18, s50, 0x4900
	s_addc_u32 s19, s51, 0
	s_add_u32 s20, s50, 0x4a00
	s_addc_u32 s21, s51, 0
	s_add_u32 s22, s50, 0x4b00
	s_addc_u32 s23, s51, 0
	s_add_u32 s24, s50, 0x4c00
	s_addc_u32 s25, s51, 0
	s_add_u32 s26, s50, 0x4d00
	s_addc_u32 s27, s51, 0
	s_add_u32 s28, s50, 0x4e00
	s_addc_u32 s29, s51, 0
	s_add_u32 s30, s50, 0x4f00
	s_addc_u32 s31, s51, 0
	s_add_u32 s34, s50, 0x5000
	s_addc_u32 s35, s51, 0
	s_add_u32 s36, s50, 0x5100
	s_addc_u32 s37, s51, 0
	s_add_u32 s38, s50, 0x5200
	s_addc_u32 s39, s51, 0
	s_add_u32 s40, s50, 0x5300
	s_addc_u32 s41, s51, 0
	s_mov_b32 s33, 1
	v_mov_b32_e32 v17, 0
	s_branch .LBB0_76
